# combined variant + nt (streaming) stores for the final f32 output
# speedup vs baseline: 1.0049x; 1.0049x over previous
; __device__ __forceinline__ unsigned pkbf(float lo, float hi) { return pg8::cvt_pk_bf16(lo, hi); }
; __device__ __forceinline__ void unpack8bf(const u32x4 w, float* f) { f[0] = bflo(w.x); f[1] = bfhi(w.x); f[2] = bflo(w.y); f[3] = bfhi(w.y); f[4] = bflo(w.z); f[5] = bfhi(w.z); f[6] = bflo(w.w); f[7] = bfhi(w.w); }
; __device__ __forceinline__ void norm_row_bf(const bf16_t* src, const float* gain, bf16_t* ob, float* of, int lane) {
;     float v[16]; float s = 0.f;
;     const u32x4 w0 = *((const u32x4*)src + lane), w1 = *((const u32x4*)src + lane + 64);
;     unpack8bf(w0, v); unpack8bf(w1, v + 8);
; #pragma unroll
;     for (int e = 0; e < 16; ++e) s += v[e] * v[e];
;     const float rstd = 1.0f / sqrtf(wave_sum(s) * (1.f / DM) + NORM_EPS);
; #pragma unroll
;     for (int h = 0; h < 2; ++h) { const float* g = gain + h * 512 + lane * 8; const f32x4 g0 = *(const f32x4*)g, g1 = *(const f32x4*)(g + 4);
;         float o[8];
; #pragma unroll
;         for (int e = 0; e < 4; ++e) { o[e] = v[h * 8 + e] * rstd * g0[e]; o[4 + e] = v[h * 8 + 4 + e] * rstd * g1[e]; }
;         if (ob) { u32x4 w; w.x = pkbf(o[0], o[1]); w.y = pkbf(o[2], o[3]); w.z = pkbf(o[4], o[5]); w.w = pkbf(o[6], o[7]); *((u32x4*)ob + lane + 64 * h) = w; }
;         else { const f32x4 a = {o[0], o[1], o[2], o[3]}, b = {o[4], o[5], o[6], o[7]}; *(f32x4*)(of + h * 512 + lane * 8) = a; *(f32x4*)(of + h * 512 + lane * 8 + 4) = b; } }
; }
.LBB0_1501:
	global_load_dwordx4 v[14:17], v[2:3], off
	global_load_dwordx4 v[18:21], v[2:3], off offset:1024
	global_load_dwordx4 v[22:25], v[0:1], off offset:16
	global_load_dwordx4 v[26:29], v[0:1], off
	s_add_i32 s34, s34, s88
	v_lshl_add_u64 v[2:3], v[2:3], 0, s[2:3]
	s_cmp_gt_i32 s34, 0xbfff
	s_waitcnt vmcnt(3)
	v_lshlrev_b32_e32 v34, 16, v14
	v_and_b32_e32 v35, 0xffff0000, v14
	v_lshlrev_b32_e32 v14, 16, v15
	v_and_b32_e32 v15, 0xffff0000, v15
	v_pk_mul_f32 v[44:45], v[34:35], v[34:35]
	v_pk_mul_f32 v[46:47], v[14:15], v[14:15]
	v_add_f32_e32 v44, v44, v45
	v_lshlrev_b32_e32 v32, 16, v16
	v_and_b32_e32 v33, 0xffff0000, v16
	v_add_f32_e32 v44, v46, v44
	s_waitcnt vmcnt(2)
	v_and_b32_e32 v30, 0xffff0000, v21
	v_lshlrev_b32_e32 v31, 16, v21
	v_lshlrev_b32_e32 v36, 16, v20
	v_and_b32_e32 v37, 0xffff0000, v20
	v_pk_mul_f32 v[20:21], v[32:33], v[32:33]
	v_add_f32_e32 v44, v47, v44
	v_lshlrev_b32_e32 v16, 16, v17
	v_and_b32_e32 v17, 0xffff0000, v17
	v_add_f32_e32 v20, v20, v44
	v_pk_mul_f32 v[42:43], v[16:17], v[16:17]
	v_add_f32_e32 v20, v21, v20
	v_lshlrev_b32_e32 v38, 16, v18
	v_and_b32_e32 v39, 0xffff0000, v18
	v_add_f32_e32 v20, v42, v20
	v_pk_mul_f32 v[50:51], v[38:39], v[38:39]
	v_add_f32_e32 v20, v43, v20
	v_lshlrev_b32_e32 v40, 16, v19
	v_and_b32_e32 v41, 0xffff0000, v19
	v_add_f32_e32 v20, v50, v20
	v_pk_mul_f32 v[52:53], v[40:41], v[40:41]
	v_add_f32_e32 v20, v51, v20
	v_add_f32_e32 v20, v52, v20
	v_pk_mul_f32 v[48:49], v[36:37], v[36:37]
	v_add_f32_e32 v20, v53, v20
	v_add_f32_e32 v20, v48, v20
	v_pk_mul_f32 v[18:19], v[30:31], v[30:31]
	v_add_f32_e32 v20, v49, v20
	v_add_f32_e32 v19, v19, v20
	v_add_f32_e32 v18, v18, v19
	ds_bpermute_b32 v19, v6, v18
	s_waitcnt lgkmcnt(0)
	v_add_f32_e32 v18, v18, v19
	ds_bpermute_b32 v19, v7, v18
	s_waitcnt lgkmcnt(0)
	v_add_f32_e32 v18, v18, v19
	ds_bpermute_b32 v19, v8, v18
	s_waitcnt lgkmcnt(0)
	v_add_f32_e32 v18, v18, v19
	ds_bpermute_b32 v19, v9, v18
	s_waitcnt lgkmcnt(0)
	v_add_f32_e32 v18, v18, v19
	ds_bpermute_b32 v19, v10, v18
	s_waitcnt lgkmcnt(0)
	v_add_f32_e32 v18, v18, v19
	ds_bpermute_b32 v19, v11, v18
	s_waitcnt lgkmcnt(0)
	v_add_f32_e32 v18, v18, v19
	v_fmamk_f32 v18, v18, 0x3a800000, v12
	v_mul_f32_e32 v19, 0x4f800000, v18
	v_cmp_gt_f32_e32 vcc, s6, v18
	s_nop 1
	v_cndmask_b32_e32 v18, v18, v19, vcc
	v_sqrt_f32_e32 v19, v18
	s_nop 0
	v_add_u32_e32 v20, -1, v19
	v_add_u32_e32 v21, 1, v19
	v_fma_f32 v42, -v20, v19, v18
	v_fma_f32 v43, -v21, v19, v18
	v_cmp_ge_f32_e64 s[0:1], 0, v42
	s_nop 1
	v_cndmask_b32_e64 v19, v19, v20, s[0:1]
	v_cmp_lt_f32_e64 s[0:1], 0, v43
	s_nop 1
	v_cndmask_b32_e64 v19, v19, v21, s[0:1]
	v_mul_f32_e32 v20, 0x37800000, v19
	v_cndmask_b32_e32 v19, v19, v20, vcc
	v_cmp_class_f32_e32 vcc, v18, v13
	s_nop 1
	v_cndmask_b32_e32 v18, v19, v18, vcc
	v_div_scale_f32 v19, s[0:1], v18, v18, 1.0
	v_rcp_f32_e32 v21, v19
	v_div_scale_f32 v20, vcc, 1.0, v18, 1.0
	v_fma_f32 v42, -v19, v21, 1.0
	v_fmac_f32_e32 v21, v42, v21
	v_mul_f32_e32 v42, v20, v21
	v_fma_f32 v43, -v19, v42, v20
	v_fmac_f32_e32 v42, v43, v21
	v_fma_f32 v19, -v19, v42, v20
	v_div_fmas_f32 v19, v19, v21, v42
	v_div_fixup_f32 v42, v19, v18, 1.0
	v_pk_mul_f32 v[18:19], v[42:43], v[34:35] op_sel_hi:[0,1]
	v_pk_mul_f32 v[14:15], v[42:43], v[14:15] op_sel_hi:[0,1]
	v_pk_mul_f32 v[32:33], v[42:43], v[32:33] op_sel_hi:[0,1]
	v_pk_mul_f32 v[20:21], v[42:43], v[16:17] op_sel_hi:[0,1]
	s_waitcnt vmcnt(0)
	v_pk_mul_f32 v[16:17], v[28:29], v[14:15]
	v_pk_mul_f32 v[14:15], v[26:27], v[18:19]
	v_pk_mul_f32 v[20:21], v[24:25], v[20:21]
	v_pk_mul_f32 v[18:19], v[22:23], v[32:33]
	global_store_dwordx4 v[4:5], v[14:17], off nt
	global_store_dwordx4 v[4:5], v[18:21], off offset:16 nt
	global_load_dwordx4 v[14:17], v[0:1], off offset:2048
	s_nop 0
	global_load_dwordx4 v[18:21], v[0:1], off offset:2064
	v_pk_mul_f32 v[26:27], v[42:43], v[40:41] op_sel_hi:[0,1]
	v_pk_mul_f32 v[28:29], v[42:43], v[38:39] op_sel_hi:[0,1]
	v_pk_mul_f32 v[22:23], v[42:43], v[36:37] op_sel_hi:[0,1]
	v_pk_mul_f32 v[24:25], v[42:43], v[30:31] op_sel_hi:[0,1]
	s_waitcnt vmcnt(1)
	v_pk_mul_f32 v[14:15], v[14:15], v[28:29]
	v_pk_mul_f32 v[16:17], v[16:17], v[26:27]
	s_waitcnt vmcnt(0)
	v_pk_mul_f32 v[18:19], v[18:19], v[22:23]
	v_pk_mul_f32 v[20:21], v[20:21], v[24:25] op_sel:[0,1] op_sel_hi:[1,0]
	global_store_dwordx4 v[4:5], v[14:17], off offset:2048 nt
	global_store_dwordx4 v[4:5], v[18:21], off offset:2064 nt
	v_lshl_add_u64 v[4:5], v[4:5], 0, s[4:5]
	s_cbranch_scc0 .LBB0_1501
